# fold phase: modulation-vector reduction moved to blocks without a fold item (512-block grid); gMLP epilogue gain vector loaded once in a batch
# speedup vs baseline: 1.0017x; 1.0017x over previous
.LBB0_162:
	s_mov_b32 s0, s76
	s_cmp_eq_u32 s82, 0x200
	s_cbranch_scc0 .Lmr_gen
	s_sub_i32 s0, s76, 0x100
	s_cmp_lt_i32 s0, 0
	s_cselect_b32 s0, 0x1000, s0
.Lmr_gen:
	v_mov_b32_e32 v0, v231
	s_waitcnt lgkmcnt(0)
	s_barrier
	ds_read_b64 v[4:5], v1 offset:63760
	ds_read_b64 v[2:3], v1 offset:63760
	v_lshl_add_u32 v0, s0, 8, v0
	s_mov_b32 s0, 0x9000
	s_lshl_b32 s74, s82, 8
	v_cmp_gt_i32_e32 vcc, s0, v0
	s_and_saveexec_b64 s[0:1], vcc
	s_cbranch_execz .LBB0_165
	v_mov_b32_e32 v1, 0
	ds_read_b64 v[6:7], v1 offset:63552
	s_mov_b64 s[2:3], 0x2a20000
	s_waitcnt lgkmcnt(0)
	v_lshl_add_u64 v[2:3], v[2:3], 0, s[2:3]
	s_mov_b64 s[2:3], 0x27e0000
	v_ashrrev_i32_e32 v1, 31, v0
	s_ashr_i32 s75, s74, 31
	v_lshl_add_u64 v[4:5], v[4:5], 0, s[2:3]
	v_lshlrev_b64 v[8:9], 2, v[0:1]
	s_lshl_b64 s[2:3], s[74:75], 2
	s_mov_b64 s[4:5], 0
	s_mov_b32 s6, 0x2aaaaaab
	s_movk_i32 s7, 0x1800
	s_mov_b32 s8, 0x38e38e39
	s_mov_b32 s9, 0x24000
	s_mov_b32 s10, 0x48000
	s_mov_b32 s11, 0x6c000
	s_mov_b32 s12, 0x90000
	s_mov_b32 s13, 0xb4000
	s_mov_b32 s14, 0xd8000
	s_mov_b32 s15, 0xfc000
	s_mov_b32 s16, 0x120000
	s_mov_b32 s17, 0x144000
	s_mov_b32 s18, 0x168000
	s_mov_b32 s19, 0x18c000
	s_mov_b32 s20, 0x1b0000
	s_mov_b32 s21, 0x1d4000
	s_mov_b32 s22, 0x1f8000
	s_mov_b32 s24, 0x8fff
